# merge: bf16 running sum of the first 128-row half kept in 32 VGPRs across the 3 K segments (no M round trip for that half); 22 long-lived constants parked in dead workspace during the phase
# speedup vs baseline: 1.0098x; 1.0098x over previous
.LBB0_661:
	s_or_b64 exec, exec, s[0:1]
	v_readlane_b32 s2, v253, 46
	v_readlane_b32 s3, v253, 47
	s_mov_b64 s[0:1], 0
	v_mov_b32_e32 v14, v197
	s_waitcnt lgkmcnt(0)
	v_cndmask_b32_e64 v0, 0, 1, s[2:3]
	s_barrier
	s_barrier
	v_cmp_ne_u32_e64 s[4:5], 1, v0
	s_andn2_b64 vcc, exec, s[2:3]
	v_readfirstlane_b32 s2, v14
	s_cbranch_vccnz .LBB0_707
	s_lshl_b32 s87, s52, 11
	v_lshl_add_u32 v243, v197, 2, s87
	s_add_u32 s88, s96, 0x6100000
	s_addc_u32 s89, s97, 0
	global_store_dword v243, v196, s[88:89]
	s_add_u32 s88, s88, 0x80000
	s_addc_u32 s89, s89, 0
	global_store_dword v243, v198, s[88:89]
	s_add_u32 s88, s88, 0x80000
	s_addc_u32 s89, s89, 0
	global_store_dword v243, v199, s[88:89]
	s_add_u32 s88, s88, 0x80000
	s_addc_u32 s89, s89, 0
	global_store_dword v243, v200, s[88:89]
	s_add_u32 s88, s88, 0x80000
	s_addc_u32 s89, s89, 0
	global_store_dword v243, v201, s[88:89]
	s_add_u32 s88, s88, 0x80000
	s_addc_u32 s89, s89, 0
	global_store_dword v243, v218, s[88:89]
	s_add_u32 s88, s88, 0x80000
	s_addc_u32 s89, s89, 0
	global_store_dword v243, v219, s[88:89]
	s_add_u32 s88, s88, 0x80000
	s_addc_u32 s89, s89, 0
	global_store_dword v243, v220, s[88:89]
	s_add_u32 s88, s88, 0x80000
	s_addc_u32 s89, s89, 0
	global_store_dword v243, v222, s[88:89]
	s_add_u32 s88, s88, 0x80000
	s_addc_u32 s89, s89, 0
	global_store_dword v243, v223, s[88:89]
	s_add_u32 s88, s88, 0x80000
	s_addc_u32 s89, s89, 0
	global_store_dword v243, v224, s[88:89]
	s_add_u32 s88, s88, 0x80000
	s_addc_u32 s89, s89, 0
	global_store_dword v243, v225, s[88:89]
	s_add_u32 s88, s88, 0x80000
	s_addc_u32 s89, s89, 0
	global_store_dword v243, v226, s[88:89]
	s_add_u32 s88, s88, 0x80000
	s_addc_u32 s89, s89, 0
	global_store_dword v243, v227, s[88:89]
	s_add_u32 s88, s88, 0x80000
	s_addc_u32 s89, s89, 0
	global_store_dword v243, v228, s[88:89]
	s_add_u32 s88, s88, 0x80000
	s_addc_u32 s89, s89, 0
	global_store_dword v243, v229, s[88:89]
	s_add_u32 s88, s88, 0x80000
	s_addc_u32 s89, s89, 0
	global_store_dword v243, v230, s[88:89]
	s_add_u32 s88, s88, 0x80000
	s_addc_u32 s89, s89, 0
	global_store_dword v243, v231, s[88:89]
	s_add_u32 s88, s88, 0x80000
	s_addc_u32 s89, s89, 0
	global_store_dword v243, v232, s[88:89]
	s_add_u32 s88, s88, 0x80000
	s_addc_u32 s89, s89, 0
	global_store_dword v243, v233, s[88:89]
	s_add_u32 s88, s88, 0x80000
	s_addc_u32 s89, s89, 0
	global_store_dword v243, v234, s[88:89]
	s_add_u32 s88, s88, 0x80000
	s_addc_u32 s89, s89, 0
	global_store_dword v243, v235, s[88:89]
	s_add_u32 s88, s88, 0x80000
	s_addc_u32 s89, s89, 0
	v_lshlrev_b32_e32 v0, 4, v14
	v_add_u32_e32 v1, 0x2000, v0
	v_ashrrev_i32_e32 v2, 31, v1
	v_lshrrev_b32_e32 v2, 22, v2
	v_add_u32_e32 v2, v1, v2
	v_ashrrev_i32_e32 v8, 10, v2
	v_mul_i32_i24_e32 v3, 0x400, v8
	v_sub_u32_e32 v1, v1, v3
	v_lshrrev_b32_e32 v3, 4, v1
	v_bitop3_b32 v1, v3, v1, 32 bitop3:0x6c
	v_ashrrev_i32_e32 v3, 31, v1
	v_lshrrev_b32_e32 v3, 26, v3
	v_add_u32_e32 v3, v1, v3
	v_ashrrev_i32_e32 v9, 6, v3
	v_and_b32_e32 v3, 0xc0, v3
	v_sub_u32_e32 v1, v1, v3
	v_lshlrev_b32_e32 v2, 5, v8
	v_ashrrev_i16_sdwa v1, v221, sext(v1) dst_sel:DWORD dst_unused:UNUSED_PAD src0_sel:DWORD src1_sel:BYTE_0
	v_and_b32_e32 v2, 32, v2
	v_bfe_i32 v10, v1, 0, 16
	v_add_u32_e32 v1, v2, v10
	v_lshlrev_b32_e32 v2, 3, v8
	v_and_b32_e32 v2, 0x1ffff0, v2
	v_add_lshl_u32 v2, v9, v2, 11
	v_lshl_add_u32 v204, v1, 1, v2
	v_bfe_i32 v2, v14, 27, 1
	v_lshrrev_b32_e32 v2, 22, v2
	v_add_u32_e32 v2, v0, v2
	v_and_b32_e32 v2, 0xfffffc00, v2
	s_add_u32 s3, s96, s0
	v_sub_u32_e32 v0, v0, v2
	s_addc_u32 s18, s97, s1
	v_lshrrev_b32_e32 v2, 4, v0
	s_add_u32 s19, s3, 0xd000000
	v_bitop3_b32 v2, v2, v0, 32 bitop3:0x6c
	v_ashrrev_i32_e32 v0, 31, v0
	s_addc_u32 s20, s18, 0
	s_lshl_b32 s0, s50, 21
	v_lshrrev_b32_e32 v0, 26, v0
	s_add_u32 s0, s3, s0
	v_ashrrev_i32_e32 v1, 31, v14
	v_add_u32_e32 v0, v2, v0
	s_addc_u32 s1, s18, 0
	v_lshrrev_b32_e32 v1, 26, v1
	v_ashrrev_i32_e32 v12, 6, v0
	s_add_u32 s21, s0, 0x10100000
	v_add_u32_e32 v1, v14, v1
	v_mul_i32_i24_e32 v0, 64, v12
	s_addc_u32 s22, s1, 0
	s_ashr_i32 s6, s2, 6
	v_ashrrev_i32_e32 v11, 6, v1
	v_sub_u32_e32 v0, v2, v0
	s_ashr_i32 s7, s2, 8
	s_lshl_b32 s23, s6, 10
	v_lshlrev_b32_e32 v1, 5, v11
	v_ashrrev_i16_sdwa v0, v221, sext(v0) dst_sel:DWORD dst_unused:UNUSED_PAD src0_sel:DWORD src1_sel:BYTE_0
	s_add_u32 s8, s19, s65
	v_and_b32_e32 v1, 32, v1
	v_bfe_i32 v13, v0, 0, 16
	s_addc_u32 s9, s20, 0
	v_add_u32_e32 v0, v1, v13
	v_lshlrev_b32_e32 v1, 3, v11
	s_add_u32 s14, s21, s66
	v_and_b32_e32 v1, 0x1ffff0, v1
	s_addc_u32 s15, s22, 0
	v_add_lshl_u32 v1, v12, v1, 11
	s_add_i32 s24, s23, 0
	v_lshl_add_u32 v194, v0, 1, v1
	s_add_i32 m0, s24, 0x10000
	s_add_i32 s25, s24, 0x2000
	global_load_lds_dwordx4 v194, s[14:15]
	s_add_i32 m0, s24, 0x12000
	s_add_u32 s0, s14, 0x40000
	global_load_lds_dwordx4 v204, s[14:15]
	s_mov_b32 m0, s24
	s_addc_u32 s1, s15, 0
	global_load_lds_dwordx4 v194, s[8:9]
	s_mov_b32 m0, s25
	v_mov_b32_e32 v205, v195
	global_load_lds_dwordx4 v204, s[8:9]
	s_add_i32 m0, s24, 0x14000
	v_lshl_add_u64 v[6:7], s[14:15], 0, v[194:195]
	global_load_lds_dwordx4 v194, s[0:1]
	s_add_i32 m0, s24, 0x16000
	v_lshl_add_u64 v[4:5], s[14:15], 0, v[204:205]
	global_load_lds_dwordx4 v204, s[0:1]
	s_add_u32 s0, s8, 0x40000
	s_addc_u32 s1, s9, 0
	s_add_i32 s26, s24, 0x4000
	s_mov_b32 m0, s26
	s_add_i32 s27, s24, 0x6000
	global_load_lds_dwordx4 v194, s[0:1]
	s_mov_b32 m0, s27
	v_lshl_add_u64 v[2:3], s[8:9], 0, v[194:195]
	global_load_lds_dwordx4 v204, s[0:1]
	s_cmp_lg_u32 s7, 1
	v_lshl_add_u64 v[0:1], s[8:9], 0, v[204:205]
	s_cbranch_scc1 .LBB0_664
	s_barrier

.LBB0_670:
	s_add_i32 s44, s14, 2
	s_add_u32 s15, s8, 0xfffc0080
	s_addc_u32 s16, s9, -1
	s_add_i32 s45, 0, 0x10000
	v_add_u32_e32 v140, s45, v237
	ds_read_b128 v[128:131], v140
	ds_read_b128 v[132:135], v140 offset:1024
	ds_read_b128 v[136:139], v140 offset:2048
	ds_read_b128 v[140:143], v140 offset:3072
	s_cmp_eq_u32 s41, s14
	s_cselect_b32 s14, s12, s42
	s_cselect_b32 s17, s11, s16
	s_cselect_b32 s16, s10, s15
	s_cselect_b32 s15, s13, s43
	v_lshl_add_u64 v[176:177], s[8:9], 0, v[206:207]
	s_add_i32 m0, s24, 0xc000
	ds_read_b128 v[144:147], v242
	ds_read_b128 v[148:151], v242 offset:1024
	ds_read_b128 v[152:155], v242 offset:2048
	ds_read_b128 v[156:159], v242 offset:3072
	ds_read_b128 v[160:163], v242 offset:4096
	ds_read_b128 v[164:167], v242 offset:5120
	ds_read_b128 v[168:171], v242 offset:6144
	ds_read_b128 v[172:175], v242 offset:7168
	global_load_lds_dwordx4 v[176:177], off
	v_lshl_add_u64 v[176:177], s[8:9], 0, v[208:209]
	s_add_i32 m0, s24, 0xe000
	s_nop 0
	global_load_lds_dwordx4 v[176:177], off
	s_waitcnt lgkmcnt(8)
	s_barrier
	s_waitcnt lgkmcnt(0)
	s_setprio 1
	s_waitcnt lgkmcnt(0)
	v_mfma_f32_16x16x32_bf16 v[124:127], v[128:131], v[144:147], v[124:127]
	v_mfma_f32_16x16x32_bf16 v[120:123], v[136:139], v[144:147], v[120:123]
	v_mfma_f32_16x16x32_bf16 v[112:115], v[128:131], v[152:155], v[112:115]
	v_mfma_f32_16x16x32_bf16 v[104:107], v[136:139], v[152:155], v[104:107]
	v_mfma_f32_16x16x32_bf16 v[96:99], v[128:131], v[160:163], v[96:99]
	v_mfma_f32_16x16x32_bf16 v[88:91], v[136:139], v[160:163], v[88:91]
	v_mfma_f32_16x16x32_bf16 v[80:83], v[128:131], v[168:171], v[80:83]
	v_mfma_f32_16x16x32_bf16 v[72:75], v[136:139], v[168:171], v[72:75]
	v_mfma_f32_16x16x32_bf16 v[124:127], v[132:135], v[148:151], v[124:127]
	v_mfma_f32_16x16x32_bf16 v[120:123], v[140:143], v[148:151], v[120:123]
	v_mfma_f32_16x16x32_bf16 v[112:115], v[132:135], v[156:159], v[112:115]
	v_mfma_f32_16x16x32_bf16 v[104:107], v[140:143], v[156:159], v[104:107]
	v_mfma_f32_16x16x32_bf16 v[96:99], v[132:135], v[164:167], v[96:99]
	v_mfma_f32_16x16x32_bf16 v[88:91], v[140:143], v[164:167], v[88:91]
	v_mfma_f32_16x16x32_bf16 v[80:83], v[132:135], v[172:175], v[80:83]
	v_mfma_f32_16x16x32_bf16 v[72:75], v[140:143], v[172:175], v[72:75]
	s_setprio 0
	s_barrier
	s_add_i32 s48, 0, 0x14000
	s_add_i32 s45, s45, s23
	v_add_u32_e32 v188, s48, v237
	v_lshl_add_u64 v[192:193], s[14:15], 0, v[194:195]
	s_mov_b32 m0, s45
	ds_read_b128 v[176:179], v188
	ds_read_b128 v[180:183], v188 offset:1024
	ds_read_b128 v[184:187], v188 offset:2048
	ds_read_b128 v[188:191], v188 offset:3072
	global_load_lds_dwordx4 v[192:193], off
	v_lshl_add_u64 v[210:211], s[14:15], 0, v[204:205]
	s_add_i32 m0, s45, 0x2000
	s_nop 0
	global_load_lds_dwordx4 v[210:211], off
	s_barrier
	s_waitcnt lgkmcnt(0)
	s_setprio 1
	s_waitcnt lgkmcnt(0)
	v_mfma_f32_16x16x32_bf16 v[116:119], v[176:179], v[144:147], v[116:119]
	v_mfma_f32_16x16x32_bf16 v[108:111], v[184:187], v[144:147], v[108:111]
	v_mfma_f32_16x16x32_bf16 v[100:103], v[176:179], v[152:155], v[100:103]
	v_mfma_f32_16x16x32_bf16 v[92:95], v[184:187], v[152:155], v[92:95]
	v_mfma_f32_16x16x32_bf16 v[84:87], v[176:179], v[160:163], v[84:87]
	v_mfma_f32_16x16x32_bf16 v[76:79], v[184:187], v[160:163], v[76:79]
	v_mfma_f32_16x16x32_bf16 v[68:71], v[176:179], v[168:171], v[68:71]
	v_mfma_f32_16x16x32_bf16 v[64:67], v[184:187], v[168:171], v[64:67]
	v_mfma_f32_16x16x32_bf16 v[116:119], v[180:183], v[148:151], v[116:119]
	v_mfma_f32_16x16x32_bf16 v[108:111], v[188:191], v[148:151], v[108:111]
	v_mfma_f32_16x16x32_bf16 v[100:103], v[180:183], v[156:159], v[100:103]
	v_mfma_f32_16x16x32_bf16 v[92:95], v[188:191], v[156:159], v[92:95]
	v_mfma_f32_16x16x32_bf16 v[84:87], v[180:183], v[164:167], v[84:87]
	v_mfma_f32_16x16x32_bf16 v[76:79], v[188:191], v[164:167], v[76:79]
	v_mfma_f32_16x16x32_bf16 v[68:71], v[180:183], v[172:175], v[68:71]
	v_mfma_f32_16x16x32_bf16 v[64:67], v[188:191], v[172:175], v[64:67]
	s_setprio 0
	s_mov_b32 m0, s24
	v_lshl_add_u64 v[212:213], s[16:17], 0, v[194:195]
	s_barrier
	ds_read_b128 v[144:147], v242 offset:16384
	ds_read_b128 v[148:151], v242 offset:17408
	ds_read_b128 v[152:155], v242 offset:18432
	ds_read_b128 v[156:159], v242 offset:19456
	ds_read_b128 v[160:163], v242 offset:20480
	ds_read_b128 v[164:167], v242 offset:21504
	ds_read_b128 v[168:171], v242 offset:22528
	ds_read_b128 v[172:175], v242 offset:23552
	global_load_lds_dwordx4 v[212:213], off
	v_lshl_add_u64 v[214:215], s[16:17], 0, v[204:205]
	s_mov_b32 m0, s25
	s_nop 0
	global_load_lds_dwordx4 v[214:215], off
	s_barrier
	s_waitcnt lgkmcnt(0)
	s_setprio 1
	s_waitcnt lgkmcnt(0)
	v_mfma_f32_16x16x32_bf16 v[60:63], v[128:131], v[144:147], v[60:63]
	v_mfma_f32_16x16x32_bf16 v[56:59], v[136:139], v[144:147], v[56:59]
	v_mfma_f32_16x16x32_bf16 v[48:51], v[128:131], v[152:155], v[48:51]
	v_mfma_f32_16x16x32_bf16 v[40:43], v[136:139], v[152:155], v[40:43]
	v_mfma_f32_16x16x32_bf16 v[32:35], v[128:131], v[160:163], v[32:35]
	v_mfma_f32_16x16x32_bf16 v[24:27], v[136:139], v[160:163], v[24:27]
	v_mfma_f32_16x16x32_bf16 v[16:19], v[128:131], v[168:171], v[16:19]
	v_mfma_f32_16x16x32_bf16 v[8:11], v[136:139], v[168:171], v[8:11]
	v_mfma_f32_16x16x32_bf16 v[60:63], v[132:135], v[148:151], v[60:63]
	v_mfma_f32_16x16x32_bf16 v[56:59], v[140:143], v[148:151], v[56:59]
	v_mfma_f32_16x16x32_bf16 v[48:51], v[132:135], v[156:159], v[48:51]
	v_mfma_f32_16x16x32_bf16 v[40:43], v[140:143], v[156:159], v[40:43]
	v_mfma_f32_16x16x32_bf16 v[32:35], v[132:135], v[164:167], v[32:35]
	v_mfma_f32_16x16x32_bf16 v[24:27], v[140:143], v[164:167], v[24:27]
	v_mfma_f32_16x16x32_bf16 v[16:19], v[132:135], v[172:175], v[16:19]
	v_mfma_f32_16x16x32_bf16 v[8:11], v[140:143], v[172:175], v[8:11]
	s_setprio 0
	s_barrier
	s_add_u32 s46, s14, 0x40000
	s_addc_u32 s47, s15, 0
	s_add_i32 s45, s48, s23
	v_lshl_add_u64 v[128:129], s[46:47], 0, v[194:195]
	s_mov_b32 m0, s45
	s_nop 0
	global_load_lds_dwordx4 v[128:129], off
	v_lshl_add_u64 v[128:129], s[46:47], 0, v[204:205]
	s_add_i32 m0, s45, 0x2000
	s_nop 0
	global_load_lds_dwordx4 v[128:129], off
	s_waitcnt vmcnt(6)
	s_barrier
	s_setprio 1
	v_mfma_f32_16x16x32_bf16 v[52:55], v[176:179], v[144:147], v[52:55]
	v_mfma_f32_16x16x32_bf16 v[44:47], v[184:187], v[144:147], v[44:47]
	v_mfma_f32_16x16x32_bf16 v[36:39], v[176:179], v[152:155], v[36:39]
	v_mfma_f32_16x16x32_bf16 v[28:31], v[184:187], v[152:155], v[28:31]
	v_mfma_f32_16x16x32_bf16 v[20:23], v[176:179], v[160:163], v[20:23]
	v_mfma_f32_16x16x32_bf16 v[12:15], v[184:187], v[160:163], v[12:15]
	v_mfma_f32_16x16x32_bf16 v[4:7], v[176:179], v[168:171], v[4:7]
	v_mfma_f32_16x16x32_bf16 v[0:3], v[184:187], v[168:171], v[0:3]
	v_mfma_f32_16x16x32_bf16 v[52:55], v[180:183], v[148:151], v[52:55]
	v_mfma_f32_16x16x32_bf16 v[44:47], v[188:191], v[148:151], v[44:47]
	v_mfma_f32_16x16x32_bf16 v[36:39], v[180:183], v[156:159], v[36:39]
	v_mfma_f32_16x16x32_bf16 v[28:31], v[188:191], v[156:159], v[28:31]
	v_mfma_f32_16x16x32_bf16 v[20:23], v[180:183], v[164:167], v[20:23]
	v_mfma_f32_16x16x32_bf16 v[12:15], v[188:191], v[164:167], v[12:15]
	v_mfma_f32_16x16x32_bf16 v[4:7], v[180:183], v[172:175], v[4:7]
	v_mfma_f32_16x16x32_bf16 v[0:3], v[188:191], v[172:175], v[0:3]
	s_setprio 0
	s_add_i32 s45, 0, 0x18000
	v_add_u32_e32 v140, s45, v237
	s_barrier
	ds_read_b128 v[128:131], v140
	ds_read_b128 v[132:135], v140 offset:1024
	ds_read_b128 v[136:139], v140 offset:2048
	ds_read_b128 v[140:143], v140 offset:3072
	s_add_u32 s16, s16, 0x40000
	s_addc_u32 s17, s17, 0
	s_mov_b32 m0, s26
	v_lshl_add_u64 v[176:177], s[16:17], 0, v[194:195]
	ds_read_b128 v[144:147], v242 offset:32768
	ds_read_b128 v[148:151], v242 offset:33792
	ds_read_b128 v[152:155], v242 offset:34816
	ds_read_b128 v[156:159], v242 offset:35840
	ds_read_b128 v[160:163], v242 offset:36864
	ds_read_b128 v[164:167], v242 offset:37888
	ds_read_b128 v[168:171], v242 offset:38912
	ds_read_b128 v[172:175], v242 offset:39936
	global_load_lds_dwordx4 v[176:177], off
	v_lshl_add_u64 v[176:177], s[16:17], 0, v[204:205]
	s_mov_b32 m0, s27
	s_nop 0
	global_load_lds_dwordx4 v[176:177], off
	s_waitcnt lgkmcnt(8)
	s_barrier
	s_waitcnt lgkmcnt(0)
	s_setprio 1
	s_waitcnt lgkmcnt(0)
	v_mfma_f32_16x16x32_bf16 v[124:127], v[128:131], v[144:147], v[124:127]
	v_mfma_f32_16x16x32_bf16 v[120:123], v[136:139], v[144:147], v[120:123]
	v_mfma_f32_16x16x32_bf16 v[112:115], v[128:131], v[152:155], v[112:115]
	v_mfma_f32_16x16x32_bf16 v[104:107], v[136:139], v[152:155], v[104:107]
	v_mfma_f32_16x16x32_bf16 v[96:99], v[128:131], v[160:163], v[96:99]
	v_mfma_f32_16x16x32_bf16 v[88:91], v[136:139], v[160:163], v[88:91]
	v_mfma_f32_16x16x32_bf16 v[80:83], v[128:131], v[168:171], v[80:83]
	v_mfma_f32_16x16x32_bf16 v[72:75], v[136:139], v[168:171], v[72:75]
	v_mfma_f32_16x16x32_bf16 v[124:127], v[132:135], v[148:151], v[124:127]
	v_mfma_f32_16x16x32_bf16 v[120:123], v[140:143], v[148:151], v[120:123]
	v_mfma_f32_16x16x32_bf16 v[112:115], v[132:135], v[156:159], v[112:115]
	v_mfma_f32_16x16x32_bf16 v[104:107], v[140:143], v[156:159], v[104:107]
	v_mfma_f32_16x16x32_bf16 v[96:99], v[132:135], v[164:167], v[96:99]
	v_mfma_f32_16x16x32_bf16 v[88:91], v[140:143], v[164:167], v[88:91]
	v_mfma_f32_16x16x32_bf16 v[80:83], v[132:135], v[172:175], v[80:83]
	v_mfma_f32_16x16x32_bf16 v[72:75], v[140:143], v[172:175], v[72:75]
	s_setprio 0
	s_barrier
	s_add_i32 s16, 0, 0x1c000
	s_add_i32 s17, s45, s23
	v_add_u32_e32 v188, s16, v237
	v_lshl_add_u64 v[192:193], v[192:193], 0, s[82:83]
	s_mov_b32 m0, s17
	ds_read_b128 v[176:179], v188
	ds_read_b128 v[180:183], v188 offset:1024
	ds_read_b128 v[184:187], v188 offset:2048
	ds_read_b128 v[188:191], v188 offset:3072
	global_load_lds_dwordx4 v[192:193], off
	v_lshl_add_u64 v[192:193], v[210:211], 0, s[82:83]
	s_add_i32 m0, s17, 0x2000
	s_nop 0
	global_load_lds_dwordx4 v[192:193], off
	s_barrier
	s_waitcnt lgkmcnt(0)
	s_setprio 1
	s_waitcnt lgkmcnt(0)
	v_mfma_f32_16x16x32_bf16 v[116:119], v[176:179], v[144:147], v[116:119]
	v_mfma_f32_16x16x32_bf16 v[108:111], v[184:187], v[144:147], v[108:111]
	v_mfma_f32_16x16x32_bf16 v[100:103], v[176:179], v[152:155], v[100:103]
	v_mfma_f32_16x16x32_bf16 v[92:95], v[184:187], v[152:155], v[92:95]
	v_mfma_f32_16x16x32_bf16 v[84:87], v[176:179], v[160:163], v[84:87]
	v_mfma_f32_16x16x32_bf16 v[76:79], v[184:187], v[160:163], v[76:79]
	v_mfma_f32_16x16x32_bf16 v[68:71], v[176:179], v[168:171], v[68:71]
	v_mfma_f32_16x16x32_bf16 v[64:67], v[184:187], v[168:171], v[64:67]
	v_mfma_f32_16x16x32_bf16 v[116:119], v[180:183], v[148:151], v[116:119]
	v_mfma_f32_16x16x32_bf16 v[108:111], v[188:191], v[148:151], v[108:111]
	v_mfma_f32_16x16x32_bf16 v[100:103], v[180:183], v[156:159], v[100:103]
	v_mfma_f32_16x16x32_bf16 v[92:95], v[188:191], v[156:159], v[92:95]
	v_mfma_f32_16x16x32_bf16 v[84:87], v[180:183], v[164:167], v[84:87]
	v_mfma_f32_16x16x32_bf16 v[76:79], v[188:191], v[164:167], v[76:79]
	v_mfma_f32_16x16x32_bf16 v[68:71], v[180:183], v[172:175], v[68:71]
	v_mfma_f32_16x16x32_bf16 v[64:67], v[188:191], v[172:175], v[64:67]
	s_setprio 0
	s_mov_b32 m0, s28
	v_lshl_add_u64 v[192:193], v[212:213], 0, s[82:83]
	s_barrier
	ds_read_b128 v[144:147], v242 offset:49152
	ds_read_b128 v[148:151], v242 offset:50176
	ds_read_b128 v[152:155], v242 offset:51200
	ds_read_b128 v[156:159], v242 offset:52224
	ds_read_b128 v[160:163], v242 offset:53248
	ds_read_b128 v[164:167], v242 offset:54272
	ds_read_b128 v[168:171], v242 offset:55296
	ds_read_b128 v[172:175], v242 offset:56320
	global_load_lds_dwordx4 v[192:193], off
	v_lshl_add_u64 v[192:193], v[214:215], 0, s[82:83]
	s_mov_b32 m0, s29
	s_nop 0
	global_load_lds_dwordx4 v[192:193], off
	s_barrier
	s_waitcnt lgkmcnt(0)
	s_setprio 1
	s_waitcnt lgkmcnt(0)
	v_mfma_f32_16x16x32_bf16 v[60:63], v[128:131], v[144:147], v[60:63]
	v_mfma_f32_16x16x32_bf16 v[56:59], v[136:139], v[144:147], v[56:59]
	v_mfma_f32_16x16x32_bf16 v[48:51], v[128:131], v[152:155], v[48:51]
	v_mfma_f32_16x16x32_bf16 v[40:43], v[136:139], v[152:155], v[40:43]
	v_mfma_f32_16x16x32_bf16 v[32:35], v[128:131], v[160:163], v[32:35]
	v_mfma_f32_16x16x32_bf16 v[24:27], v[136:139], v[160:163], v[24:27]
	v_mfma_f32_16x16x32_bf16 v[16:19], v[128:131], v[168:171], v[16:19]
	v_mfma_f32_16x16x32_bf16 v[8:11], v[136:139], v[168:171], v[8:11]
	v_mfma_f32_16x16x32_bf16 v[60:63], v[132:135], v[148:151], v[60:63]
	v_mfma_f32_16x16x32_bf16 v[56:59], v[140:143], v[148:151], v[56:59]
	v_mfma_f32_16x16x32_bf16 v[48:51], v[132:135], v[156:159], v[48:51]
	v_mfma_f32_16x16x32_bf16 v[40:43], v[140:143], v[156:159], v[40:43]
	v_mfma_f32_16x16x32_bf16 v[32:35], v[132:135], v[164:167], v[32:35]
	v_mfma_f32_16x16x32_bf16 v[24:27], v[140:143], v[164:167], v[24:27]
	v_mfma_f32_16x16x32_bf16 v[16:19], v[132:135], v[172:175], v[16:19]
	v_mfma_f32_16x16x32_bf16 v[8:11], v[140:143], v[172:175], v[8:11]
	s_setprio 0
	s_barrier
	s_add_u32 s14, s14, 0x40080
	s_addc_u32 s15, s15, 0
	s_add_i32 s16, s16, s23
	v_lshl_add_u64 v[128:129], s[14:15], 0, v[194:195]
	s_mov_b32 m0, s16
	s_nop 0
	global_load_lds_dwordx4 v[128:129], off
	v_lshl_add_u64 v[128:129], s[14:15], 0, v[204:205]
	s_add_i32 m0, s16, 0x2000
	s_nop 0
	global_load_lds_dwordx4 v[128:129], off
	s_waitcnt vmcnt(6)
	s_barrier
	s_setprio 1
	v_mfma_f32_16x16x32_bf16 v[52:55], v[176:179], v[144:147], v[52:55]
	v_mfma_f32_16x16x32_bf16 v[44:47], v[184:187], v[144:147], v[44:47]
	v_mfma_f32_16x16x32_bf16 v[36:39], v[176:179], v[152:155], v[36:39]
	v_mfma_f32_16x16x32_bf16 v[28:31], v[184:187], v[152:155], v[28:31]
	v_mfma_f32_16x16x32_bf16 v[20:23], v[176:179], v[160:163], v[20:23]
	v_mfma_f32_16x16x32_bf16 v[12:15], v[184:187], v[160:163], v[12:15]
	v_mfma_f32_16x16x32_bf16 v[4:7], v[176:179], v[168:171], v[4:7]
	v_mfma_f32_16x16x32_bf16 v[0:3], v[184:187], v[168:171], v[0:3]
	v_mfma_f32_16x16x32_bf16 v[52:55], v[180:183], v[148:151], v[52:55]
	v_mfma_f32_16x16x32_bf16 v[44:47], v[188:191], v[148:151], v[44:47]
	v_mfma_f32_16x16x32_bf16 v[36:39], v[180:183], v[156:159], v[36:39]
	v_mfma_f32_16x16x32_bf16 v[28:31], v[188:191], v[156:159], v[28:31]
	v_mfma_f32_16x16x32_bf16 v[20:23], v[180:183], v[164:167], v[20:23]
	v_mfma_f32_16x16x32_bf16 v[12:15], v[188:191], v[164:167], v[12:15]
	v_mfma_f32_16x16x32_bf16 v[4:7], v[180:183], v[172:175], v[4:7]
	v_mfma_f32_16x16x32_bf16 v[0:3], v[188:191], v[172:175], v[0:3]
	s_setprio 0
	s_add_u32 s8, s8, 0x100
	s_addc_u32 s9, s9, 0
	s_add_u32 s42, s42, 0x100
	s_addc_u32 s43, s43, 0
	s_cmp_ge_i32 s44, s40
	s_mov_b32 s14, s44
	s_barrier
	s_cbranch_scc0 .LBB0_670
	s_lshl_b32 s8, s37, 10
	s_ashr_i32 s9, s8, 31
	s_cmp_gt_i32 s37, 0
	s_cselect_b64 s[16:17], -1, 0
	s_lshl_b32 s39, s39, 8
	s_lshl_b64 s[8:9], s[8:9], 1
	s_add_u32 s14, s3, s8
	s_addc_u32 s15, s18, s9
	v_add_u32_e32 v210, s39, v236
	v_lshl_or_b32 v212, s38, 8, v241
	v_mov_b64_e32 v[128:129], s[14:15]
	v_mad_i64_i32 v[128:129], s[8:9], v210, s81, v[128:129]
	v_ashrrev_i32_e32 v213, 31, v212
	v_lshl_add_u64 v[130:131], v[212:213], 1, v[128:129]
	global_load_dwordx4 v[186:189], v[130:131], off
	v_ashrrev_i32_e32 v211, 31, v210
	v_lshlrev_b64 v[128:129], 11, v[210:211]
	v_lshl_add_u64 v[214:215], s[0:1], 0, v[128:129]
	s_cmp_lt_i32 s37, 1
	v_lshl_add_u64 v[128:129], v[212:213], 1, v[214:215]
	s_cbranch_scc1 .LBB0_673
	v_mov_b32_e32 v190, v243
	v_mov_b32_e32 v191, v244
	v_mov_b32_e32 v192, v245
	v_mov_b32_e32 v193, v246
	s_branch .LBB0_674

.LBB0_674:
	global_load_dwordx4 v[178:181], v[130:131], off offset:256
	v_cndmask_b32_e64 v130, 0, 1, s[16:17]
	v_mov_b32_e32 v158, 0
	v_cmp_ne_u32_e64 s[8:9], 1, v130
	s_andn2_b64 vcc, exec, s[16:17]
	v_mov_b32_e32 v182, 0
	v_mov_b32_e32 v183, 0
	v_mov_b32_e32 v184, 0
	v_mov_b32_e32 v185, 0
	s_cbranch_vccnz .LBB0_676
	v_mov_b32_e32 v182, v247
	v_mov_b32_e32 v183, v248
	v_mov_b32_e32 v184, v249
	v_mov_b32_e32 v185, v250
.LBB0_676:
	v_or_b32_e32 v128, 16, v210
	v_mov_b64_e32 v[130:131], s[14:15]
	v_mad_i64_i32 v[130:131], s[16:17], v128, s81, v[130:131]
	v_lshl_add_u64 v[130:131], v[212:213], 1, v[130:131]
	global_load_dwordx4 v[174:177], v[130:131], off
	v_ashrrev_i32_e32 v129, 31, v128
	v_lshlrev_b64 v[128:129], 11, v[128:129]
	v_lshl_add_u64 v[128:129], s[0:1], 0, v[128:129]
	s_and_b64 vcc, exec, s[8:9]
	v_lshl_add_u64 v[128:129], v[212:213], 1, v[128:129]
	v_mov_b32_e32 v159, 0
	v_mov_b32_e32 v160, 0
	v_mov_b32_e32 v161, 0
	s_cbranch_vccnz .LBB0_678
	v_mov_b32_e32 v158, v251
	v_mov_b32_e32 v159, v255
	v_mov_b32_e32 v160, v196
	v_mov_b32_e32 v161, v198
.LBB0_678:
	global_load_dwordx4 v[166:169], v[130:131], off offset:256
	v_mov_b32_e32 v146, 0
	s_and_b64 vcc, exec, s[8:9]
	v_mov_b32_e32 v170, 0
	v_mov_b32_e32 v171, 0
	v_mov_b32_e32 v172, 0
	v_mov_b32_e32 v173, 0
	s_cbranch_vccnz .LBB0_680
	v_mov_b32_e32 v170, v199
	v_mov_b32_e32 v171, v200
	v_mov_b32_e32 v172, v201
	v_mov_b32_e32 v173, v218
.LBB0_680:
	v_or_b32_e32 v128, 32, v210
	v_mov_b64_e32 v[130:131], s[14:15]
	v_mad_i64_i32 v[130:131], s[16:17], v128, s81, v[130:131]
	v_lshl_add_u64 v[130:131], v[212:213], 1, v[130:131]
	global_load_dwordx4 v[162:165], v[130:131], off
	v_ashrrev_i32_e32 v129, 31, v128
	v_lshlrev_b64 v[128:129], 11, v[128:129]
	v_lshl_add_u64 v[128:129], s[0:1], 0, v[128:129]
	s_and_b64 vcc, exec, s[8:9]
	v_lshl_add_u64 v[128:129], v[212:213], 1, v[128:129]
	v_mov_b32_e32 v147, 0
	v_mov_b32_e32 v148, 0
	v_mov_b32_e32 v149, 0
	s_cbranch_vccnz .LBB0_682
	v_mov_b32_e32 v146, v219
	v_mov_b32_e32 v147, v220
	v_mov_b32_e32 v148, v222
	v_mov_b32_e32 v149, v223
.LBB0_682:
	global_load_dwordx4 v[150:153], v[130:131], off offset:256
	v_mov_b32_e32 v130, 0
	s_and_b64 vcc, exec, s[8:9]
	v_mov_b32_e32 v154, 0
	v_mov_b32_e32 v155, 0
	v_mov_b32_e32 v156, 0
	v_mov_b32_e32 v157, 0
	s_cbranch_vccnz .LBB0_684
	v_mov_b32_e32 v154, v224
	v_mov_b32_e32 v155, v225
	v_mov_b32_e32 v156, v226
	v_mov_b32_e32 v157, v227
.LBB0_684:
	v_or_b32_e32 v132, 48, v210
	v_mov_b64_e32 v[128:129], s[14:15]
	v_mad_i64_i32 v[128:129], s[16:17], v132, s81, v[128:129]
	v_lshl_add_u64 v[128:129], v[212:213], 1, v[128:129]
	global_load_dwordx4 v[142:145], v[128:129], off
	v_ashrrev_i32_e32 v133, 31, v132
	v_lshlrev_b64 v[132:133], 11, v[132:133]
	v_lshl_add_u64 v[132:133], s[0:1], 0, v[132:133]
	s_and_b64 vcc, exec, s[8:9]
	v_lshl_add_u64 v[216:217], v[212:213], 1, v[132:133]
	v_mov_b32_e32 v131, 0
	v_mov_b32_e32 v132, 0
	v_mov_b32_e32 v133, 0
	s_cbranch_vccnz .LBB0_686
	v_mov_b32_e32 v130, v228
	v_mov_b32_e32 v131, v229
	v_mov_b32_e32 v132, v230
	v_mov_b32_e32 v133, v231
.LBB0_686:
	global_load_dwordx4 v[134:137], v[128:129], off offset:256
	v_mov_b32_e32 v128, 0
	s_and_b64 vcc, exec, s[8:9]
	v_mov_b32_e32 v138, 0
	v_mov_b32_e32 v139, 0
	v_mov_b32_e32 v140, 0
	v_mov_b32_e32 v141, 0
	s_cbranch_vccnz .LBB0_688
	v_mov_b32_e32 v138, v232
	v_mov_b32_e32 v139, v233
	v_mov_b32_e32 v140, v234
	v_mov_b32_e32 v141, v235
.LBB0_688:
	s_waitcnt vmcnt(0)
	v_lshlrev_b32_e32 v129, 16, v190
	v_lshlrev_b32_e32 v211, 16, v186
	v_fmac_f32_e32 v129, v124, v211
	v_and_b32_e32 v124, 0xffff0000, v190
	v_and_b32_e32 v186, 0xffff0000, v186
	v_fmac_f32_e32 v124, v125, v186
	v_cvt_pk_bf16_f32 v186, v129, v124
	v_lshlrev_b32_e32 v124, 16, v191
	v_lshlrev_b32_e32 v125, 16, v187
	v_fmac_f32_e32 v124, v126, v125
	v_and_b32_e32 v125, 0xffff0000, v191
	v_and_b32_e32 v126, 0xffff0000, v187
	v_fmac_f32_e32 v125, v127, v126
	v_cvt_pk_bf16_f32 v187, v124, v125
	v_lshlrev_b32_e32 v124, 16, v192
	v_lshlrev_b32_e32 v125, 16, v188
	v_fmac_f32_e32 v124, v120, v125
	v_and_b32_e32 v120, 0xffff0000, v192
	v_and_b32_e32 v125, 0xffff0000, v188
	v_fmac_f32_e32 v120, v121, v125
	v_cvt_pk_bf16_f32 v188, v124, v120
	v_lshlrev_b32_e32 v120, 16, v193
	v_lshlrev_b32_e32 v121, 16, v189
	v_fmac_f32_e32 v120, v122, v121
	v_and_b32_e32 v121, 0xffff0000, v193
	v_and_b32_e32 v122, 0xffff0000, v189
	v_fmac_f32_e32 v121, v123, v122
	v_lshlrev_b32_e32 v122, 16, v182
	v_lshlrev_b32_e32 v123, 16, v178
	v_lshlrev_b64 v[124:125], 1, v[212:213]
	v_fmac_f32_e32 v122, v116, v123
	v_and_b32_e32 v116, 0xffff0000, v182
	v_and_b32_e32 v123, 0xffff0000, v178
	v_cvt_pk_bf16_f32 v189, v120, v121
	v_lshl_add_u64 v[120:121], v[214:215], 0, v[124:125]
	v_fmac_f32_e32 v116, v117, v123
	v_mov_b32_e32 v243, v186
	v_mov_b32_e32 v244, v187
	v_mov_b32_e32 v245, v188
	v_mov_b32_e32 v246, v189
	s_cmp_lg_u32 s37, 2
	s_cbranch_scc1 .Lmrs_0
	global_store_dwordx4 v[120:121], v[186:189], off
.Lmrs_0:
	v_cvt_pk_bf16_f32 v116, v122, v116
	v_lshlrev_b32_e32 v117, 16, v183
	v_lshlrev_b32_e32 v122, 16, v179
	v_fmac_f32_e32 v117, v118, v122
	v_and_b32_e32 v118, 0xffff0000, v183
	v_and_b32_e32 v122, 0xffff0000, v179
	v_fmac_f32_e32 v118, v119, v122
	v_cvt_pk_bf16_f32 v117, v117, v118
	v_lshlrev_b32_e32 v118, 16, v184
	v_lshlrev_b32_e32 v119, 16, v180
	v_fmac_f32_e32 v118, v108, v119
	v_and_b32_e32 v108, 0xffff0000, v184
	v_and_b32_e32 v119, 0xffff0000, v180
	v_fmac_f32_e32 v108, v109, v119
	v_cvt_pk_bf16_f32 v118, v118, v108
	v_lshlrev_b32_e32 v108, 16, v185
	v_lshlrev_b32_e32 v109, 16, v181
	v_fmac_f32_e32 v108, v110, v109
	v_and_b32_e32 v109, 0xffff0000, v185
	v_and_b32_e32 v110, 0xffff0000, v181
	v_fmac_f32_e32 v109, v111, v110
	v_cvt_pk_bf16_f32 v119, v108, v109
	v_lshlrev_b32_e32 v108, 16, v158
	v_lshlrev_b32_e32 v109, 16, v174
	v_fmac_f32_e32 v108, v112, v109
	v_and_b32_e32 v109, 0xffff0000, v158
	v_and_b32_e32 v110, 0xffff0000, v174
	v_fmac_f32_e32 v109, v113, v110
	v_mov_b32_e32 v247, v116
	v_mov_b32_e32 v248, v117
	v_mov_b32_e32 v249, v118
	v_mov_b32_e32 v250, v119
	s_cmp_lg_u32 s37, 2
	s_cbranch_scc1 .Lmrs_1
	global_store_dwordx4 v[120:121], v[116:119], off offset:256
.Lmrs_1:
	v_cvt_pk_bf16_f32 v108, v108, v109
	v_lshlrev_b32_e32 v109, 16, v159
	v_lshlrev_b32_e32 v110, 16, v175
	v_fmac_f32_e32 v109, v114, v110
	v_and_b32_e32 v110, 0xffff0000, v159
	v_and_b32_e32 v111, 0xffff0000, v175
	v_fmac_f32_e32 v110, v115, v111
	v_cvt_pk_bf16_f32 v109, v109, v110
	v_lshlrev_b32_e32 v110, 16, v160
	v_lshlrev_b32_e32 v111, 16, v176
	v_fmac_f32_e32 v110, v104, v111
	v_and_b32_e32 v104, 0xffff0000, v160
	v_and_b32_e32 v111, 0xffff0000, v176
	v_fmac_f32_e32 v104, v105, v111
	v_cvt_pk_bf16_f32 v110, v110, v104
	v_lshlrev_b32_e32 v104, 16, v161
	v_lshlrev_b32_e32 v105, 16, v177
	v_add_u32_e32 v116, s39, v238
	v_fmac_f32_e32 v104, v106, v105
	v_and_b32_e32 v105, 0xffff0000, v161
	v_and_b32_e32 v106, 0xffff0000, v177
	v_fmac_f32_e32 v105, v107, v106
	v_ashrrev_i32_e32 v117, 31, v116
	v_cvt_pk_bf16_f32 v111, v104, v105
	v_lshlrev_b64 v[104:105], 11, v[116:117]
	v_lshlrev_b32_e32 v106, 16, v170
	v_lshlrev_b32_e32 v107, 16, v166
	v_lshl_add_u64 v[104:105], s[0:1], 0, v[104:105]
	v_fmac_f32_e32 v106, v100, v107
	v_and_b32_e32 v100, 0xffff0000, v170
	v_and_b32_e32 v107, 0xffff0000, v166
	v_lshl_add_u64 v[104:105], v[104:105], 0, v[124:125]
	v_fmac_f32_e32 v100, v101, v107
	v_mov_b32_e32 v251, v108
	v_mov_b32_e32 v255, v109
	v_mov_b32_e32 v196, v110
	v_mov_b32_e32 v198, v111
	s_cmp_lg_u32 s37, 2
	s_cbranch_scc1 .Lmrs_2
	global_store_dwordx4 v[104:105], v[108:111], off
.Lmrs_2:
	v_cvt_pk_bf16_f32 v100, v106, v100
	v_lshlrev_b32_e32 v101, 16, v171
	v_lshlrev_b32_e32 v106, 16, v167
	v_fmac_f32_e32 v101, v102, v106
	v_and_b32_e32 v102, 0xffff0000, v171
	v_and_b32_e32 v106, 0xffff0000, v167
	v_fmac_f32_e32 v102, v103, v106
	v_cvt_pk_bf16_f32 v101, v101, v102
	v_lshlrev_b32_e32 v102, 16, v172
	v_lshlrev_b32_e32 v103, 16, v168
	v_fmac_f32_e32 v102, v92, v103
	v_and_b32_e32 v92, 0xffff0000, v172
	v_and_b32_e32 v103, 0xffff0000, v168
	v_fmac_f32_e32 v92, v93, v103
	v_cvt_pk_bf16_f32 v102, v102, v92
	v_lshlrev_b32_e32 v92, 16, v173
	v_lshlrev_b32_e32 v93, 16, v169
	v_fmac_f32_e32 v92, v94, v93
	v_and_b32_e32 v93, 0xffff0000, v173
	v_and_b32_e32 v94, 0xffff0000, v169
	v_fmac_f32_e32 v93, v95, v94
	v_cvt_pk_bf16_f32 v103, v92, v93
	v_lshlrev_b32_e32 v92, 16, v146
	v_lshlrev_b32_e32 v93, 16, v162
	v_fmac_f32_e32 v92, v96, v93
	v_and_b32_e32 v93, 0xffff0000, v146
	v_and_b32_e32 v94, 0xffff0000, v162
	v_fmac_f32_e32 v93, v97, v94
	v_mov_b32_e32 v199, v100
	v_mov_b32_e32 v200, v101
	v_mov_b32_e32 v201, v102
	v_mov_b32_e32 v218, v103
	s_cmp_lg_u32 s37, 2
	s_cbranch_scc1 .Lmrs_3
	global_store_dwordx4 v[104:105], v[100:103], off offset:256
.Lmrs_3:
	v_cvt_pk_bf16_f32 v92, v92, v93
	v_lshlrev_b32_e32 v93, 16, v147
	v_lshlrev_b32_e32 v94, 16, v163
	v_fmac_f32_e32 v93, v98, v94
	v_and_b32_e32 v94, 0xffff0000, v147
	v_and_b32_e32 v95, 0xffff0000, v163
	v_fmac_f32_e32 v94, v99, v95
	v_cvt_pk_bf16_f32 v93, v93, v94
	v_lshlrev_b32_e32 v94, 16, v148
	v_lshlrev_b32_e32 v95, 16, v164
	v_fmac_f32_e32 v94, v88, v95
	v_and_b32_e32 v88, 0xffff0000, v148
	v_and_b32_e32 v95, 0xffff0000, v164
	v_fmac_f32_e32 v88, v89, v95
	v_cvt_pk_bf16_f32 v94, v94, v88
	v_lshlrev_b32_e32 v88, 16, v149
	v_lshlrev_b32_e32 v89, 16, v165
	v_add_u32_e32 v100, s39, v239
	v_fmac_f32_e32 v88, v90, v89
	v_and_b32_e32 v89, 0xffff0000, v149
	v_and_b32_e32 v90, 0xffff0000, v165
	v_fmac_f32_e32 v89, v91, v90
	v_ashrrev_i32_e32 v101, 31, v100
	v_cvt_pk_bf16_f32 v95, v88, v89
	v_lshlrev_b64 v[88:89], 11, v[100:101]
	v_lshlrev_b32_e32 v90, 16, v154
	v_lshlrev_b32_e32 v91, 16, v150
	v_lshl_add_u64 v[88:89], s[0:1], 0, v[88:89]
	v_fmac_f32_e32 v90, v84, v91
	v_and_b32_e32 v84, 0xffff0000, v154
	v_and_b32_e32 v91, 0xffff0000, v150
	v_lshl_add_u64 v[88:89], v[88:89], 0, v[124:125]
	v_fmac_f32_e32 v84, v85, v91
	v_mov_b32_e32 v219, v92
	v_mov_b32_e32 v220, v93
	v_mov_b32_e32 v222, v94
	v_mov_b32_e32 v223, v95
	s_cmp_lg_u32 s37, 2
	s_cbranch_scc1 .Lmrs_4
	global_store_dwordx4 v[88:89], v[92:95], off
.Lmrs_4:
	v_cvt_pk_bf16_f32 v84, v90, v84
	v_lshlrev_b32_e32 v85, 16, v155
	v_lshlrev_b32_e32 v90, 16, v151
	v_fmac_f32_e32 v85, v86, v90
	v_and_b32_e32 v86, 0xffff0000, v155
	v_and_b32_e32 v90, 0xffff0000, v151
	v_fmac_f32_e32 v86, v87, v90
	v_cvt_pk_bf16_f32 v85, v85, v86
	v_lshlrev_b32_e32 v86, 16, v156
	v_lshlrev_b32_e32 v87, 16, v152
	v_fmac_f32_e32 v86, v76, v87
	v_and_b32_e32 v76, 0xffff0000, v156
	v_and_b32_e32 v87, 0xffff0000, v152
	v_fmac_f32_e32 v76, v77, v87
	v_cvt_pk_bf16_f32 v86, v86, v76
	v_lshlrev_b32_e32 v76, 16, v157
	v_lshlrev_b32_e32 v77, 16, v153
	v_fmac_f32_e32 v76, v78, v77
	v_and_b32_e32 v77, 0xffff0000, v157
	v_and_b32_e32 v78, 0xffff0000, v153
	v_fmac_f32_e32 v77, v79, v78
	v_cvt_pk_bf16_f32 v87, v76, v77
	v_lshlrev_b32_e32 v76, 16, v130
	v_lshlrev_b32_e32 v77, 16, v142
	v_fmac_f32_e32 v76, v80, v77
	v_and_b32_e32 v77, 0xffff0000, v130
	v_and_b32_e32 v78, 0xffff0000, v142
	v_fmac_f32_e32 v77, v81, v78
	v_mov_b32_e32 v224, v84
	v_mov_b32_e32 v225, v85
	v_mov_b32_e32 v226, v86
	v_mov_b32_e32 v227, v87
	s_cmp_lg_u32 s37, 2
	s_cbranch_scc1 .Lmrs_5
	global_store_dwordx4 v[88:89], v[84:87], off offset:256
.Lmrs_5:
	v_cvt_pk_bf16_f32 v76, v76, v77
	v_lshlrev_b32_e32 v77, 16, v131
	v_lshlrev_b32_e32 v78, 16, v143
	v_fmac_f32_e32 v77, v82, v78
	v_and_b32_e32 v78, 0xffff0000, v131
	v_and_b32_e32 v79, 0xffff0000, v143
	v_fmac_f32_e32 v78, v83, v79
	v_cvt_pk_bf16_f32 v77, v77, v78
	v_lshlrev_b32_e32 v78, 16, v132
	v_lshlrev_b32_e32 v79, 16, v144
	v_fmac_f32_e32 v78, v72, v79
	v_and_b32_e32 v72, 0xffff0000, v132
	v_and_b32_e32 v79, 0xffff0000, v144
	v_fmac_f32_e32 v72, v73, v79
	v_cvt_pk_bf16_f32 v78, v78, v72
	v_lshlrev_b32_e32 v72, 16, v133
	v_lshlrev_b32_e32 v73, 16, v145
	v_add_u32_e32 v84, s39, v240
	v_fmac_f32_e32 v72, v74, v73
	v_and_b32_e32 v73, 0xffff0000, v133
	v_and_b32_e32 v74, 0xffff0000, v145
	v_fmac_f32_e32 v73, v75, v74
	v_ashrrev_i32_e32 v85, 31, v84
	v_cvt_pk_bf16_f32 v79, v72, v73
	v_lshlrev_b64 v[72:73], 11, v[84:85]
	v_lshl_add_u64 v[72:73], s[0:1], 0, v[72:73]
	v_lshl_add_u64 v[80:81], v[72:73], 0, v[124:125]
	v_lshlrev_b32_e32 v72, 16, v138
	v_lshlrev_b32_e32 v73, 16, v134
	v_fmac_f32_e32 v72, v68, v73
	v_and_b32_e32 v68, 0xffff0000, v138
	v_and_b32_e32 v73, 0xffff0000, v134
	v_fmac_f32_e32 v68, v69, v73
	v_mov_b32_e32 v228, v76
	v_mov_b32_e32 v229, v77
	v_mov_b32_e32 v230, v78
	v_mov_b32_e32 v231, v79
	s_cmp_lg_u32 s37, 2
	s_cbranch_scc1 .Lmrs_6
	global_store_dwordx4 v[80:81], v[76:79], off
.Lmrs_6:
	v_cvt_pk_bf16_f32 v72, v72, v68
	v_lshlrev_b32_e32 v68, 16, v139
	v_lshlrev_b32_e32 v69, 16, v135
	v_fmac_f32_e32 v68, v70, v69
	v_and_b32_e32 v69, 0xffff0000, v139
	v_and_b32_e32 v70, 0xffff0000, v135
	v_fmac_f32_e32 v69, v71, v70
	v_cvt_pk_bf16_f32 v73, v68, v69
	v_lshlrev_b32_e32 v68, 16, v140
	v_lshlrev_b32_e32 v69, 16, v136
	v_fmac_f32_e32 v68, v64, v69
	v_and_b32_e32 v64, 0xffff0000, v140
	v_and_b32_e32 v69, 0xffff0000, v136
	v_fmac_f32_e32 v64, v65, v69
	v_cvt_pk_bf16_f32 v74, v68, v64
	v_lshlrev_b32_e32 v64, 16, v141
	v_lshlrev_b32_e32 v65, 16, v137
	v_fmac_f32_e32 v64, v66, v65
	v_and_b32_e32 v65, 0xffff0000, v141
	v_and_b32_e32 v66, 0xffff0000, v137
	v_fmac_f32_e32 v65, v67, v66
	v_cvt_pk_bf16_f32 v75, v64, v65
	v_add_u32_e32 v66, 0x80, v210
	v_mov_b64_e32 v[64:65], s[14:15]
	v_mad_i64_i32 v[64:65], s[16:17], v66, s81, v[64:65]
	v_lshl_add_u64 v[68:69], v[64:65], 0, v[124:125]
	global_load_dwordx4 v[120:123], v[68:69], off
	v_ashrrev_i32_e32 v67, 31, v66
	v_lshlrev_b64 v[64:65], 11, v[66:67]
	v_lshl_add_u64 v[126:127], s[0:1], 0, v[64:65]
	s_and_b64 vcc, exec, s[8:9]
	v_lshl_add_u64 v[64:65], v[212:213], 1, v[126:127]
	v_mov_b32_e32 v129, 0
	v_mov_b32_e32 v130, 0
	v_mov_b32_e32 v131, 0
	v_mov_b32_e32 v232, v72
	v_mov_b32_e32 v233, v73
	v_mov_b32_e32 v234, v74
	v_mov_b32_e32 v235, v75
	s_cmp_lg_u32 s37, 2
	s_cbranch_scc1 .Lmrs_7
	global_store_dwordx4 v[80:81], v[72:75], off offset:256
.Lmrs_7:
	s_cbranch_vccnz .LBB0_690
	global_load_dwordx4 v[128:131], v[64:65], off

.LBB0_706:
	s_movk_i32 s41, 0x70
	s_barrier
	s_lshl_b32 s87, s52, 11
	v_lshl_add_u32 v243, v197, 2, s87
	s_add_u32 s88, s96, 0x6100000
	s_addc_u32 s89, s97, 0
	global_load_dword v196, v243, s[88:89]
	s_add_u32 s88, s88, 0x80000
	s_addc_u32 s89, s89, 0
	global_load_dword v198, v243, s[88:89]
	s_add_u32 s88, s88, 0x80000
	s_addc_u32 s89, s89, 0
	global_load_dword v199, v243, s[88:89]
	s_add_u32 s88, s88, 0x80000
	s_addc_u32 s89, s89, 0
	global_load_dword v200, v243, s[88:89]
	s_add_u32 s88, s88, 0x80000
	s_addc_u32 s89, s89, 0
	global_load_dword v201, v243, s[88:89]
	s_add_u32 s88, s88, 0x80000
	s_addc_u32 s89, s89, 0
	global_load_dword v218, v243, s[88:89]
	s_add_u32 s88, s88, 0x80000
	s_addc_u32 s89, s89, 0
	global_load_dword v219, v243, s[88:89]
	s_add_u32 s88, s88, 0x80000
	s_addc_u32 s89, s89, 0
	global_load_dword v220, v243, s[88:89]
	s_add_u32 s88, s88, 0x80000
	s_addc_u32 s89, s89, 0
	global_load_dword v222, v243, s[88:89]
	s_add_u32 s88, s88, 0x80000
	s_addc_u32 s89, s89, 0
	global_load_dword v223, v243, s[88:89]
	s_add_u32 s88, s88, 0x80000
	s_addc_u32 s89, s89, 0
	global_load_dword v224, v243, s[88:89]
	s_add_u32 s88, s88, 0x80000
	s_addc_u32 s89, s89, 0
	global_load_dword v225, v243, s[88:89]
	s_add_u32 s88, s88, 0x80000
	s_addc_u32 s89, s89, 0
	global_load_dword v226, v243, s[88:89]
	s_add_u32 s88, s88, 0x80000
	s_addc_u32 s89, s89, 0
	global_load_dword v227, v243, s[88:89]
	s_add_u32 s88, s88, 0x80000
	s_addc_u32 s89, s89, 0
	global_load_dword v228, v243, s[88:89]
	s_add_u32 s88, s88, 0x80000
	s_addc_u32 s89, s89, 0
	global_load_dword v229, v243, s[88:89]
	s_add_u32 s88, s88, 0x80000
	s_addc_u32 s89, s89, 0
	global_load_dword v230, v243, s[88:89]
	s_add_u32 s88, s88, 0x80000
	s_addc_u32 s89, s89, 0
	global_load_dword v231, v243, s[88:89]
	s_add_u32 s88, s88, 0x80000
	s_addc_u32 s89, s89, 0
	global_load_dword v232, v243, s[88:89]
	s_add_u32 s88, s88, 0x80000
	s_addc_u32 s89, s89, 0
	global_load_dword v233, v243, s[88:89]
	s_add_u32 s88, s88, 0x80000
	s_addc_u32 s89, s89, 0
	global_load_dword v234, v243, s[88:89]
	s_add_u32 s88, s88, 0x80000
	s_addc_u32 s89, s89, 0
	global_load_dword v235, v243, s[88:89]
	s_add_u32 s88, s88, 0x80000
	s_addc_u32 s89, s89, 0
